# P2 pooling: nt policy on the UB row loads (dead after pooling)
# speedup vs baseline: 1.0315x; 1.0022x over previous
; __global__ void __launch_bounds__(NTHR, 2) hybrid_fwd(Args args) {
;     ...
;         const int rpb = (T + G - 1) / G, rows_per = (rpb + NWAVES - 1) / NWAVES;
;         const int gI = lane >> 4, w = 2 << gI;
;         const int t_b = hb * rpb + wave * rows_per; int nr = rpb - wave * rows_per; if (nr > rows_per) nr = rows_per; if (t_b + nr > T) nr = T - t_b;
;         u32x4 qn[16];
;         if (nr > 0) { const int sp0 = t_b & 2047, c0_ = (sp0 + 1) < w ? (sp0 + 1) : w;
; #pragma unroll
;             for (int j = 0; j < 16; ++j) qn[j] = *(const u32x4*)(UB + (size_t)(j < c0_ ? t_b - j : t_b) * 512 + lane * 8); }
;         for (int i = 0; i < nr; ++i) { const int t = t_b + i;
;             const int sp = t & 2047, cnt = (sp + 1) < w ? (sp + 1) : w;
;             u32x4 qv[16];
; #pragma unroll
;             for (int j = 0; j < 16; ++j) qv[j] = qn[j];
;             if (i + 1 < nr) { const int t1 = t + 1, sp1 = t1 & 2047, c1_ = (sp1 + 1) < w ? (sp1 + 1) : w;
; #pragma unroll
;                 for (int j = 0; j < 16; ++j) qn[j] = *(const u32x4*)(UB + (size_t)(j < c1_ ? t1 - j : t1) * 512 + lane * 8); }
.LBB0_372:
	s_add_i32 s25, s20, 0x7fff
	s_waitcnt lgkmcnt(0)
	s_waitcnt lgkmcnt(0)
	s_waitcnt lgkmcnt(0)
	s_waitcnt lgkmcnt(0)
	s_waitcnt lgkmcnt(0)
	s_waitcnt lgkmcnt(0)
	s_waitcnt lgkmcnt(0)
	s_waitcnt lgkmcnt(0)
	s_waitcnt lgkmcnt(0)
	s_waitcnt lgkmcnt(0)
	s_waitcnt lgkmcnt(0)
	s_waitcnt lgkmcnt(0)
	s_waitcnt lgkmcnt(0)
	s_waitcnt lgkmcnt(0)
	s_waitcnt lgkmcnt(0)
	s_waitcnt lgkmcnt(0)
	s_waitcnt lgkmcnt(0)
	s_waitcnt lgkmcnt(0)
	s_waitcnt lgkmcnt(0)
	s_abs_i32 s61, s20
	v_cvt_f32_u32_e32 v1, s61
	s_sub_i32 s27, 0, s61
	s_waitcnt lgkmcnt(0)
	v_rcp_iflag_f32_e32 v1, v1
	s_ashr_i32 s26, s25, 31
	s_abs_i32 s25, s25
	v_mul_f32_e32 v1, 0x4f7ffffe, v1
	v_cvt_u32_f32_e32 v1, v1
	s_xor_b32 s26, s26, s21
	s_mov_b32 s28, 1
	v_readfirstlane_b32 s62, v1
	s_mul_i32 s27, s27, s62
	s_mul_hi_u32 s10, s62, s27
	s_add_i32 s62, s62, s10
	s_mul_hi_u32 s10, s25, s62
	s_mul_i32 s11, s10, s61
	s_sub_i32 s11, s25, s11
	s_add_i32 s14, s10, 1
	s_sub_i32 s15, s11, s61
	s_cmp_ge_u32 s11, s61
	s_cselect_b32 s10, s14, s10
	s_cselect_b32 s11, s15, s11
	s_add_i32 s14, s10, 1
	s_cmp_ge_u32 s11, s61
	s_cselect_b32 s10, s14, s10
	s_xor_b32 s10, s10, s26
	s_sub_i32 s56, s10, s26
	s_add_i32 s10, s56, 7
	s_ashr_i32 s14, s10, 31
	s_lshr_b32 s14, s14, 29
	s_add_i32 s10, s10, s14
	s_ashr_i32 s14, s10, 3
	s_mul_i32 s11, s56, s24
	s_mul_i32 s15, s14, s74
	s_add_i32 s10, s15, s11
	s_sub_i32 s11, s56, s15
	s_min_i32 s57, s11, s14
	s_add_i32 s11, s57, s10
	s_sub_i32 s14, 0x8000, s10
	s_cmp_gt_i32 s11, 0x8000
	s_cselect_b32 s29, s14, s57
	v_mov_b32_e32 v0, v212
	s_cmp_lt_i32 s29, 1
	v_writelane_b32 v248, s15, 5
	s_cbranch_scc1 .LBB0_377
	s_cmp_lg_u32 s29, 16
	s_cbranch_scc1 .Lpool_orig
	s_and_b32 s98, s10, 15
	s_cmp_lg_u32 s98, 0
	s_cbranch_scc1 .Lpool_orig
	v_lshlrev_b32_e32 v0, 4, v212
	v_mov_b32_e32 v1, 0
	s_lshl_b32 s98, s10, 10
	s_add_u32 s14, s8, 0x15c00000
	s_addc_u32 s15, s9, 0
	s_add_u32 s14, s14, s98
	s_addc_u32 s15, s15, 0
	s_and_b32 s99, s10, 0x7ff
	s_sub_u32 s26, s14, 0x3000
	s_subb_u32 s27, s15, 0
	v_lshl_add_u64 v[2:3], s[26:27], 0, v[0:1]
	s_sub_u32 s26, s14, 0x1000
	s_subb_u32 s27, s15, 0
	v_lshl_add_u64 v[4:5], s[26:27], 0, v[0:1]
	s_add_u32 s26, s14, 0x1000
	s_addc_u32 s27, s15, 0
	v_lshl_add_u64 v[6:7], s[26:27], 0, v[0:1]
	s_add_u32 s26, s14, 0x3000
	s_addc_u32 s27, s15, 0
	v_lshl_add_u64 v[132:133], s[26:27], 0, v[0:1]
	s_cmp_eq_u32 s99, 0
	s_cbranch_scc1 .Lpool_ld_seqstart
	global_load_dwordx4 v[8:11], v[2:3], off offset:-3072 nt
	global_load_dwordx4 v[12:15], v[2:3], off offset:-2048 nt
	global_load_dwordx4 v[16:19], v[2:3], off offset:-1024 nt
	global_load_dwordx4 v[20:23], v[2:3], off nt
	global_load_dwordx4 v[24:27], v[2:3], off offset:1024 nt
	global_load_dwordx4 v[28:31], v[2:3], off offset:2048 nt
	global_load_dwordx4 v[32:35], v[2:3], off offset:3072 nt
	global_load_dwordx4 v[36:39], v[4:5], off offset:-4096 nt
	global_load_dwordx4 v[40:43], v[4:5], off offset:-3072 nt
	global_load_dwordx4 v[44:47], v[4:5], off offset:-2048 nt
	global_load_dwordx4 v[48:51], v[4:5], off offset:-1024 nt
	global_load_dwordx4 v[52:55], v[4:5], off nt
	global_load_dwordx4 v[56:59], v[4:5], off offset:1024 nt
	global_load_dwordx4 v[60:63], v[4:5], off offset:2048 nt
	global_load_dwordx4 v[64:67], v[4:5], off offset:3072 nt
	global_load_dwordx4 v[68:71], v[6:7], off offset:-4096 nt
	global_load_dwordx4 v[72:75], v[6:7], off offset:-3072 nt
	global_load_dwordx4 v[76:79], v[6:7], off offset:-2048 nt
	global_load_dwordx4 v[80:83], v[6:7], off offset:-1024 nt
	global_load_dwordx4 v[84:87], v[6:7], off nt
	global_load_dwordx4 v[88:91], v[6:7], off offset:1024 nt
	global_load_dwordx4 v[92:95], v[6:7], off offset:2048 nt
	global_load_dwordx4 v[96:99], v[6:7], off offset:3072 nt
	global_load_dwordx4 v[100:103], v[132:133], off offset:-4096 nt
	global_load_dwordx4 v[104:107], v[132:133], off offset:-3072 nt
	global_load_dwordx4 v[108:111], v[132:133], off offset:-2048 nt
	global_load_dwordx4 v[112:115], v[132:133], off offset:-1024 nt
	global_load_dwordx4 v[116:119], v[132:133], off nt
	global_load_dwordx4 v[120:123], v[132:133], off offset:1024 nt
	global_load_dwordx4 v[124:127], v[132:133], off offset:2048 nt
	global_load_dwordx4 v[128:131], v[132:133], off offset:3072 nt
	s_branch .Lpool_ld_done
.Lpool_ld_seqstart:
	global_load_dwordx4 v[68:71], v[6:7], off offset:-4096 nt
	global_load_dwordx4 v[72:75], v[6:7], off offset:-3072 nt
	global_load_dwordx4 v[76:79], v[6:7], off offset:-2048 nt
	global_load_dwordx4 v[80:83], v[6:7], off offset:-1024 nt
	global_load_dwordx4 v[84:87], v[6:7], off nt
	global_load_dwordx4 v[88:91], v[6:7], off offset:1024 nt
	global_load_dwordx4 v[92:95], v[6:7], off offset:2048 nt
	global_load_dwordx4 v[96:99], v[6:7], off offset:3072 nt
	global_load_dwordx4 v[100:103], v[132:133], off offset:-4096 nt
	global_load_dwordx4 v[104:107], v[132:133], off offset:-3072 nt
	global_load_dwordx4 v[108:111], v[132:133], off offset:-2048 nt
	global_load_dwordx4 v[112:115], v[132:133], off offset:-1024 nt
	global_load_dwordx4 v[116:119], v[132:133], off nt
	global_load_dwordx4 v[120:123], v[132:133], off offset:1024 nt
	global_load_dwordx4 v[124:127], v[132:133], off offset:2048 nt
	global_load_dwordx4 v[128:131], v[132:133], off offset:3072 nt
	v_mov_b32_e32 v8, 0
	v_mov_b32_e32 v9, 0
	v_mov_b32_e32 v10, 0
	v_mov_b32_e32 v11, 0
	v_mov_b32_e32 v12, 0
	v_mov_b32_e32 v13, 0
	v_mov_b32_e32 v14, 0
	v_mov_b32_e32 v15, 0
	v_mov_b32_e32 v16, 0
	v_mov_b32_e32 v17, 0
	v_mov_b32_e32 v18, 0
	v_mov_b32_e32 v19, 0
	v_mov_b32_e32 v20, 0
	v_mov_b32_e32 v21, 0
	v_mov_b32_e32 v22, 0
	v_mov_b32_e32 v23, 0
	v_mov_b32_e32 v24, 0
	v_mov_b32_e32 v25, 0
	v_mov_b32_e32 v26, 0
	v_mov_b32_e32 v27, 0
	v_mov_b32_e32 v28, 0
	v_mov_b32_e32 v29, 0
	v_mov_b32_e32 v30, 0
	v_mov_b32_e32 v31, 0
	v_mov_b32_e32 v32, 0
	v_mov_b32_e32 v33, 0
	v_mov_b32_e32 v34, 0
	v_mov_b32_e32 v35, 0
	v_mov_b32_e32 v36, 0
	v_mov_b32_e32 v37, 0
	v_mov_b32_e32 v38, 0
	v_mov_b32_e32 v39, 0
	v_mov_b32_e32 v40, 0
	v_mov_b32_e32 v41, 0
	v_mov_b32_e32 v42, 0
	v_mov_b32_e32 v43, 0
	v_mov_b32_e32 v44, 0
	v_mov_b32_e32 v45, 0
	v_mov_b32_e32 v46, 0
	v_mov_b32_e32 v47, 0
	v_mov_b32_e32 v48, 0
	v_mov_b32_e32 v49, 0
	v_mov_b32_e32 v50, 0
	v_mov_b32_e32 v51, 0
	v_mov_b32_e32 v52, 0
	v_mov_b32_e32 v53, 0
	v_mov_b32_e32 v54, 0
	v_mov_b32_e32 v55, 0
	v_mov_b32_e32 v56, 0
	v_mov_b32_e32 v57, 0
	v_mov_b32_e32 v58, 0
	v_mov_b32_e32 v59, 0
	v_mov_b32_e32 v60, 0
	v_mov_b32_e32 v61, 0
	v_mov_b32_e32 v62, 0
	v_mov_b32_e32 v63, 0
	v_mov_b32_e32 v64, 0
	v_mov_b32_e32 v65, 0
	v_mov_b32_e32 v66, 0
	v_mov_b32_e32 v67, 0
